# static s_setprio 1 for the H2 loader waves (the recurrence phase is bound by its gather loads), on top of the attention-phase raise
# baseline (speedup 1.0000x reference)
; #define H2_PRIV(cc, VT_, OI_) do { const int tok0_ = b * T + 64 * (cc); \
;         const bf16* vp_ = Z2 + (size_t)(tok0_ + (vcol >> 1)) * NH2 + 2048 + h * 128 + (vcol & 1) * 64 + 8 * fq; VT_[0] = *(const u32x4*)vp_; VT_[1] = *(const u32x4*)(vp_ + 32); \
;         _Pragma("unroll") for (int tt_ = 0; tt_ < 4; ++tt_) OI_[tt_] = OI[((size_t)((unit0 + (cc)) * 4 + tt_) * 8 + w) * 64 + lane]; } while (0)
; template <bool DRY> DI void hgrn2_phase(LAS unsigned char* L, bf16* Z2, const float* DEC, unsigned long long* OIW, int bh2, int tid) {
;     ...
;     const int bh = bh2 >> 1, w = 4 * (bh2 & 1) + (wv & 3); const bool cw = wv < 4;
;     const int b = bh >> 3, h = bh & 7, unit0 = bh * 64, vcol = 16 * w + fr;
;     u32x4 sqA[2], skA[2]; f32x4 sdA = (f32x4){0.f, 0.f, 0.f, 0.f};
;     ...
;     u32x4 vtf[2] = {(u32x4){0u, 0u, 0u, 0u}, (u32x4){0u, 0u, 0u, 0u}}; unsigned long long oi[4] = {0ull, 0ull, 0ull, 0ull};
;     u32x4 nvt[2] = {(u32x4){0u, 0u, 0u, 0u}, (u32x4){0u, 0u, 0u, 0u}}; unsigned long long noi[4] = {0ull, 0ull, 0ull, 0ull};
;     H2_LOAD(0, sqA, skA, sdA); H2_WRITE(0, sqA, skA, sdA); if (cw) H2_PRIV(0, vtf, oi);
;     H2_LOAD(1, sqA, skA, sdA); if (cw) H2_PRIV(1, nvt, noi);
.Lh2_loader:
	s_setprio 1
	s_sub_u32 s51, s50, 4
	s_cmp_eq_u32 s51, 0
	s_cselect_b32 s65, 1, 0
	v_and_b32_e32 v236, 15, v130
	v_lshrrev_b32_e32 v237, 4, v130
	s_lshl_b32 s42, s51, 2
	v_add_u32_e32 v245, s42, v237
	v_lshlrev_b32_e32 v246, 13, v245
	v_lshl_add_u32 v190, v236, 4, v246
	v_add_u32_e32 v191, 0x20000, v190
	v_add_u32_e32 v192, 0x40000, v190
	v_add_u32_e32 v193, 0x60000, v190
	v_lshlrev_b32_e32 v194, 4, v130
	s_lshl_b32 s43, s39, 2
	s_add_u32 s43, s43, s51
	s_lshl_b32 s42, s43, 4
	v_add_u32_e32 v246, s42, v236
	v_lshrrev_b32_e32 v247, 1, v246
	v_lshlrev_b32_e32 v247, 13, v247
	v_and_b32_e32 v246, 1, v246
	v_lshl_add_u32 v247, v246, 7, v247
	v_lshl_add_u32 v247, v237, 4, v247
	v_add_u32_e32 v195, 0x1000, v247
	s_lshl_b32 s42, s43, 9
	v_lshlrev_b32_e32 v246, 3, v130
	v_add_u32_e32 v246, s42, v246
	v_add_u32_e32 v198, 0x1000, v246
	v_add_u32_e32 v199, 0x3000, v246
	v_mul_u32_u24_e32 v246, 0x110, v245
	v_lshl_add_u32 v200, v236, 4, v246
	v_lshrrev_b32_e32 v246, 3, v236
	v_lshl_add_u32 v246, v245, 1, v246
	v_mul_u32_u24_e32 v246, 0x90, v246
	v_and_b32_e32 v247, 7, v236
	v_lshl_add_u32 v201, v247, 4, v246
	v_lshlrev_b32_e32 v206, 4, v130
	s_lshl_b32 s42, s51, 11
	v_lshlrev_b32_e32 v246, 4, v130
	v_add_u32_e32 v207, s42, v246
	v_lshlrev_b32_e32 v246, 3, v130
	v_add_u32_e32 v208, s42, v246
	v_add_u32_e32 v209, 0xce00, v200
	v_add_u32_e32 v232, 0xce00, v201
	v_add_u32_e32 v233, 0xce00, v206
	v_add_u32_e32 v234, 0xce00, v207
	v_add_u32_e32 v235, 0xce00, v208
	s_mov_b32 s56, 0
	s_lshl_b32 s57, s56, 19
	s_add_u32 s58, s44, s57
	s_addc_u32 s59, s45, 0
	s_lshl_b32 s57, s56, 9
	s_add_u32 s60, s46, s57
	s_addc_u32 s61, s47, 0
	s_lshl_b32 s57, s56, 14
	s_add_u32 s62, s48, s57
	s_addc_u32 s63, s49, 0
	global_load_dwordx4 v[2:5], v190, s[58:59]
	global_load_dwordx4 v[18:21], v190, s[58:59] offset:2048
	global_load_dwordx4 v[6:9], v191, s[58:59]
	global_load_dwordx4 v[22:25], v191, s[58:59] offset:2048
	global_load_dwordx4 v[10:13], v192, s[58:59]
	global_load_dwordx4 v[26:29], v192, s[58:59] offset:2048
	global_load_dwordx4 v[14:17], v193, s[58:59]
	global_load_dwordx4 v[30:33], v193, s[58:59] offset:2048
	global_load_dwordx4 v[34:37], v194, s[60:61]
	global_load_dwordx4 v[38:41], v195, s[58:59]
	global_load_dwordx4 v[42:45], v195, s[58:59] offset:64
	global_load_dwordx2 v[46:47], v198, s[62:63] offset:-4096
	global_load_dwordx2 v[48:49], v198, s[62:63]
	global_load_dwordx2 v[50:51], v199, s[62:63] offset:-4096
	global_load_dwordx2 v[52:53], v199, s[62:63]
	s_mov_b32 s56, 1
	s_lshl_b32 s57, s56, 19
	s_add_u32 s58, s44, s57
	s_addc_u32 s59, s45, 0
	s_lshl_b32 s57, s56, 9
	s_add_u32 s60, s46, s57
	s_addc_u32 s61, s47, 0
	s_lshl_b32 s57, s56, 14
	s_add_u32 s62, s48, s57
	s_addc_u32 s63, s49, 0
	global_load_dwordx4 v[54:57], v190, s[58:59]
	global_load_dwordx4 v[70:73], v190, s[58:59] offset:2048
	global_load_dwordx4 v[58:61], v191, s[58:59]
	global_load_dwordx4 v[74:77], v191, s[58:59] offset:2048
	global_load_dwordx4 v[62:65], v192, s[58:59]
	global_load_dwordx4 v[78:81], v192, s[58:59] offset:2048
	global_load_dwordx4 v[66:69], v193, s[58:59]
	global_load_dwordx4 v[82:85], v193, s[58:59] offset:2048
	global_load_dwordx4 v[86:89], v194, s[60:61]
	global_load_dwordx4 v[90:93], v195, s[58:59]
	global_load_dwordx4 v[94:97], v195, s[58:59] offset:64
	global_load_dwordx2 v[98:99], v198, s[62:63] offset:-4096
	global_load_dwordx2 v[100:101], v198, s[62:63]
	global_load_dwordx2 v[102:103], v199, s[62:63] offset:-4096
	global_load_dwordx2 v[104:105], v199, s[62:63]
	s_mov_b32 s56, 2
	s_lshl_b32 s57, s56, 19
	s_add_u32 s58, s44, s57
	s_addc_u32 s59, s45, 0
	s_lshl_b32 s57, s56, 9
	s_add_u32 s60, s46, s57
	s_addc_u32 s61, s47, 0
	s_lshl_b32 s57, s56, 14
	s_add_u32 s62, s48, s57
	s_addc_u32 s63, s49, 0
	global_load_dwordx4 v[106:109], v190, s[58:59]
	global_load_dwordx4 v[122:125], v190, s[58:59] offset:2048
	global_load_dwordx4 v[110:113], v191, s[58:59]
	global_load_dwordx4 v[126:129], v191, s[58:59] offset:2048
	global_load_dwordx4 v[114:117], v192, s[58:59]
	global_load_dwordx4 v[130:133], v192, s[58:59] offset:2048
	global_load_dwordx4 v[118:121], v193, s[58:59]
	global_load_dwordx4 v[134:137], v193, s[58:59] offset:2048
	global_load_dwordx4 v[138:141], v194, s[60:61]
	global_load_dwordx4 v[142:145], v195, s[58:59]
	global_load_dwordx4 v[146:149], v195, s[58:59] offset:64
	global_load_dwordx2 v[150:151], v198, s[62:63] offset:-4096
	global_load_dwordx2 v[152:153], v198, s[62:63]
	global_load_dwordx2 v[154:155], v199, s[62:63] offset:-4096
	global_load_dwordx2 v[156:157], v199, s[62:63]
	s_mov_b32 s56, 3
	s_lshl_b32 s57, s56, 19
	s_add_u32 s58, s44, s57
	s_addc_u32 s59, s45, 0
	s_lshl_b32 s57, s56, 9
	s_add_u32 s60, s46, s57
	s_addc_u32 s61, s47, 0
	s_lshl_b32 s57, s56, 14
	s_add_u32 s62, s48, s57
	s_addc_u32 s63, s49, 0
	global_load_dwordx4 v[158:161], v190, s[58:59]
	global_load_dwordx4 v[174:177], v190, s[58:59] offset:2048
	global_load_dwordx4 v[162:165], v191, s[58:59]
	global_load_dwordx4 v[178:181], v191, s[58:59] offset:2048
	global_load_dwordx4 v[166:169], v192, s[58:59]
	global_load_dwordx4 v[182:185], v192, s[58:59] offset:2048
	global_load_dwordx4 v[170:173], v193, s[58:59]
	global_load_dwordx4 v[186:189], v193, s[58:59] offset:2048
	global_load_dwordx4 v[212:215], v194, s[60:61]
	global_load_dwordx4 v[216:219], v195, s[58:59]
	global_load_dwordx4 v[220:223], v195, s[58:59] offset:64
	global_load_dwordx2 v[224:225], v198, s[62:63] offset:-4096
	global_load_dwordx2 v[226:227], v198, s[62:63]
	global_load_dwordx2 v[228:229], v199, s[62:63] offset:-4096
	global_load_dwordx2 v[230:231], v199, s[62:63]
	s_waitcnt vmcnt(45)
	ds_write_b128 v200, v[2:5] offset:0
	ds_write_b128 v201, v[18:21] offset:17408
	ds_write_b128 v200, v[6:9] offset:4352
	ds_write_b128 v201, v[22:25] offset:22016
	ds_write_b128 v200, v[10:13] offset:8704
	ds_write_b128 v201, v[26:29] offset:26624
	ds_write_b128 v200, v[14:17] offset:13056
	ds_write_b128 v201, v[30:33] offset:31232
	ds_write_b128 v207, v[38:41] offset:36352
	ds_write_b128 v207, v[42:45] offset:37376
	ds_write_b64 v208, v[46:47] offset:44544
	ds_write_b64 v208, v[48:49] offset:45056
	ds_write_b64 v208, v[50:51] offset:45568
	ds_write_b64 v208, v[52:53] offset:46080
	s_cmp_eq_u32 s65, 0
	s_cbranch_scc1 .Lh2l_nodec_p
	s_mov_b32 exec_hi, 0
	ds_write_b128 v206, v[34:37] offset:35840
	s_mov_b32 exec_hi, -1

; #define LBAR() do { asm volatile("s_waitcnt lgkmcnt(0)" ::: "memory"); __builtin_amdgcn_s_barrier(); asm volatile("" ::: "memory"); } while (0)
; __device__ __forceinline__ unsigned xb_add(unsigned* p, unsigned v) { return __hip_atomic_fetch_add(p, v, __ATOMIC_RELAXED, __HIP_MEMORY_SCOPE_AGENT); }
; template <bool DRY> DI void hgrn2_phase(LAS unsigned char* L, bf16* Z2, const float* DEC, unsigned long long* OIW, int bh2, int tid) {
;     ...
;         if (c + 1 < 64) H2_WRITE((c + 1) & 1, sqA, skA, sdA);
;         vtf[0] = nvt[0]; vtf[1] = nvt[1]; nvt[0] = nnvt[0]; nvt[1] = nnvt[1];
; #pragma unroll
;         for (int i = 0; i < 4; ++i) { oi[i] = noi[i]; noi[i] = nnoi[i]; }
;         sqA[0] = sqB[0]; sqA[1] = sqB[1]; skA[0] = skB[0]; skA[1] = skB[1]; sdA = sdB;
;         LBAR();
;     }
; __device__ __forceinline__ void xcd_barrier(const XcdBarrier& b) {
;     asm volatile("s_waitcnt vmcnt(0)" ::: "memory");
;     __syncthreads();
;     if (threadIdx.x == 0) {
;         unsigned* bar = b.bar;
;         __builtin_amdgcn_s_waitcnt(0);
;         unsigned nloc = b.st[0], nx = b.st[1];
;         if (nloc == 0u) { xcd_barrier_complete(bar, b.x, nloc, nx); b.st[0] = nloc; b.st[1] = nx; }
;         const unsigned old = xb_add(&bar[XB_XSUB(b.x)], 1u);
.Lh2l_nodec_u3:
	s_add_u32 s56, s64, 8
	s_min_u32 s56, s56, 63
	s_lshl_b32 s57, s56, 19
	s_add_u32 s58, s44, s57
	s_addc_u32 s59, s45, 0
	s_lshl_b32 s57, s56, 9
	s_add_u32 s60, s46, s57
	s_addc_u32 s61, s47, 0
	s_lshl_b32 s57, s56, 14
	s_add_u32 s62, s48, s57
	s_addc_u32 s63, s49, 0
	global_load_dwordx4 v[2:5], v190, s[58:59]
	global_load_dwordx4 v[18:21], v190, s[58:59] offset:2048
	global_load_dwordx4 v[6:9], v191, s[58:59]
	global_load_dwordx4 v[22:25], v191, s[58:59] offset:2048
	global_load_dwordx4 v[10:13], v192, s[58:59]
	global_load_dwordx4 v[26:29], v192, s[58:59] offset:2048
	global_load_dwordx4 v[14:17], v193, s[58:59]
	global_load_dwordx4 v[30:33], v193, s[58:59] offset:2048
	global_load_dwordx4 v[34:37], v194, s[60:61]
	global_load_dwordx4 v[38:41], v195, s[58:59]
	global_load_dwordx4 v[42:45], v195, s[58:59] offset:64
	global_load_dwordx2 v[46:47], v198, s[62:63] offset:-4096
	global_load_dwordx2 v[48:49], v198, s[62:63]
	global_load_dwordx2 v[50:51], v199, s[62:63] offset:-4096
	global_load_dwordx2 v[52:53], v199, s[62:63]
	s_waitcnt lgkmcnt(0)
	s_barrier
	s_add_u32 s64, s64, 4
	s_cmp_lt_u32 s64, 64
	s_cbranch_scc1 .Lh2l_loop
.Lh2_done:
	s_setprio 0
.LBB0_713:
	s_waitcnt vmcnt(0)
	s_waitcnt vmcnt(0) lgkmcnt(0)
	s_barrier
	s_and_saveexec_b64 s[0:1], s[80:81]
	v_readlane_b32 s26, v254, 33
	v_readlane_b32 s27, v254, 34
	s_cbranch_execz .LBB0_761
	v_readlane_b32 s2, v254, 25
	s_waitcnt vmcnt(0) expcnt(0) lgkmcnt(0)
	s_nop 0
	v_mov_b32_e32 v0, s2
	ds_read_b32 v3, v0
	v_readlane_b32 s2, v254, 26
	s_waitcnt lgkmcnt(0)
	v_cmp_ne_u32_e32 vcc, 0, v3
	v_mov_b32_e32 v0, s2
	ds_read_b32 v2, v0
	s_cbranch_vccnz .LBB0_729
	v_readlane_b32 s4, v252, 17
	v_readlane_b32 s5, v252, 18
	s_load_dwordx2 s[2:3], s[4:5], 0x4
	s_mov_b32 s9, 1
	s_waitcnt lgkmcnt(0)
	s_mul_i32 s8, s2, s29
	s_mul_i32 s8, s8, s3
	s_branch .LBB0_717
